# grid-barrier / flag poll back-off: s_sleep 1 -> s_sleep 4 at all 73 spin sites, on top of v25
# baseline (speedup 1.0000x reference)
; __device__ __forceinline__ unsigned xb_ld(unsigned* p)              { return __hip_atomic_load(p, __ATOMIC_RELAXED, __HIP_MEMORY_SCOPE_AGENT); }
; __device__ __forceinline__ void xcd_barrier_complete(unsigned* bar, unsigned x, unsigned& nloc, unsigned& nx) {
;     const unsigned G = gridDim.x * gridDim.y * gridDim.z;
;     unsigned sum, cnt, mine, sp = 0u;
;     for (;;) {
;         sum = 0u; cnt = 0u; mine = 0u;
; #pragma unroll
;         for (unsigned j = 0; j < 16; ++j) { const unsigned c = xb_ld(&bar[XB_XCNT(j)]); sum += c; cnt += (c > 0u) ? 1u : 0u; mine = (j == x) ? c : mine; }
;         if (sum == G) break;
;         __builtin_amdgcn_s_sleep(1);
;         if ((++sp & 255u) == 0u) { if (xb_ld(&bar[XB_TMO])) break; if (sp > XB_SPIN_CAP) { atomicAdd(&bar[XB_TMO], 1u); break; } }
;     }
;     nloc = mine > 0u ? mine : 1u; nx = cnt > 0u ? cnt : 1u;
; }
.LBB0_68:
	global_load_dword v17, v18, s[34:35] offset:1024 sc1
	global_load_dword v2, v18, s[34:35] offset:1280 sc1
	global_load_dword v3, v18, s[34:35] offset:1536 sc1
	global_load_dword v4, v18, s[34:35] offset:1792 sc1
	global_load_dword v5, v18, s[34:35] offset:2048 sc1
	global_load_dword v6, v18, s[34:35] offset:2304 sc1
	global_load_dword v7, v18, s[34:35] offset:2560 sc1
	global_load_dword v8, v18, s[34:35] offset:2816 sc1
	global_load_dword v9, v18, s[34:35] offset:3072 sc1
	global_load_dword v10, v18, s[34:35] offset:3328 sc1
	global_load_dword v11, v18, s[34:35] offset:3584 sc1
	global_load_dword v12, v18, s[34:35] offset:3840 sc1
	global_load_dword v13, v18, s[2:3] sc1
	global_load_dword v14, v18, s[4:5] sc1
	global_load_dword v15, v18, s[6:7] sc1
	global_load_dword v16, v18, s[8:9] sc1
	s_mov_b64 s[10:11], -1
	s_mov_b64 s[12:13], -1
	s_waitcnt vmcnt(14)
	v_add_u32_e32 v19, v2, v17
	s_waitcnt vmcnt(13)
	v_add_u32_e32 v19, v19, v3
	s_waitcnt vmcnt(12)
	v_add_u32_e32 v19, v19, v4
	s_waitcnt vmcnt(11)
	v_add_u32_e32 v19, v19, v5
	s_waitcnt vmcnt(10)
	v_add_u32_e32 v19, v19, v6
	s_waitcnt vmcnt(9)
	v_add_u32_e32 v19, v19, v7
	s_waitcnt vmcnt(8)
	v_add_u32_e32 v19, v19, v8
	s_waitcnt vmcnt(7)
	v_add_u32_e32 v19, v19, v9
	s_waitcnt vmcnt(6)
	v_add_u32_e32 v19, v19, v10
	s_waitcnt vmcnt(5)
	v_add_u32_e32 v19, v19, v11
	s_waitcnt vmcnt(4)
	v_add_u32_e32 v19, v19, v12
	s_waitcnt vmcnt(3)
	v_add_u32_e32 v19, v19, v13
	s_waitcnt vmcnt(2)
	v_add_u32_e32 v19, v19, v14
	s_waitcnt vmcnt(1)
	v_add_u32_e32 v19, v19, v15
	s_waitcnt vmcnt(0)
	v_add_u32_e32 v19, v19, v16
	v_cmp_eq_u32_e32 vcc, s24, v19
	s_cbranch_vccnz .LBB0_67
	s_and_b32 s10, s25, 0xff
	s_cmp_eq_u32 s10, 0
	s_mov_b64 s[10:11], -1
	s_mov_b64 s[22:23], -1
	s_sleep 4
	s_cbranch_scc1 .LBB0_72
	s_and_b64 vcc, exec, s[22:23]
	s_cbranch_vccz .LBB0_67

; __device__ __forceinline__ unsigned xb_ld(unsigned* p)              { return __hip_atomic_load(p, __ATOMIC_RELAXED, __HIP_MEMORY_SCOPE_AGENT); }
; __device__ __forceinline__ unsigned xb_add(unsigned* p, unsigned v) { return __hip_atomic_fetch_add(p, v, __ATOMIC_RELAXED, __HIP_MEMORY_SCOPE_AGENT); }
; #define XB_SPIN(cond, bar) do { unsigned _sp = 0; while (cond) { __builtin_amdgcn_s_sleep(1); \
;     if ((++_sp & 255u) == 0u) { if (xb_ld(&(bar)[XB_TMO])) break; if (_sp > XB_SPIN_CAP) { atomicAdd(&(bar)[XB_TMO], 1u); break; } } } } while (0)
; __device__ __forceinline__ void xcd_barrier(const XcdBarrier& b) {
;     ...
;             const unsigned og = xb_add(&bar[XB_TOP], 1u);
;             const unsigned tg = og / nx;
;             if (og + 1u == (tg + 1u) * nx) xb_add(&bar[XB_TOPGEN], 1u);
;             else XB_SPIN(xb_ld(&bar[XB_TOPGEN]) == tg, bar);
;             __builtin_amdgcn_fence(__ATOMIC_ACQUIRE, "agent");
;             xb_add(&bar[XB_XGEN(b.x)], 1u);
;             asm volatile("s_waitcnt vmcnt(0)" ::: "memory");
;         } else {
;             XB_SPIN(xb_ld(&bar[XB_XGEN(b.x)]) == gen, bar);
.LBB0_86:
	s_and_b32 s24, s26, 0xff
	s_mov_b64 s[22:23], -1
	s_cmp_lg_u32 s24, 0
	s_mov_b64 s[38:39], -1
	s_sleep 4
	s_cbranch_scc0 .LBB0_89
	s_and_b64 vcc, exec, s[38:39]
	s_cbranch_vccz .LBB0_85

; __device__ __forceinline__ unsigned xb_ld(unsigned* p)              { return __hip_atomic_load(p, __ATOMIC_RELAXED, __HIP_MEMORY_SCOPE_AGENT); }
; __device__ __forceinline__ unsigned xb_add(unsigned* p, unsigned v) { return __hip_atomic_fetch_add(p, v, __ATOMIC_RELAXED, __HIP_MEMORY_SCOPE_AGENT); }
; #define XB_SPIN(cond, bar) do { unsigned _sp = 0; while (cond) { __builtin_amdgcn_s_sleep(1); \
;     if ((++_sp & 255u) == 0u) { if (xb_ld(&(bar)[XB_TMO])) break; if (_sp > XB_SPIN_CAP) { atomicAdd(&(bar)[XB_TMO], 1u); break; } } } } while (0)
; __device__ __forceinline__ void xcd_barrier(const XcdBarrier& b) {
;     ...
;             const unsigned og = xb_add(&bar[XB_TOP], 1u);
;             const unsigned tg = og / nx;
;             if (og + 1u == (tg + 1u) * nx) xb_add(&bar[XB_TOPGEN], 1u);
;             else XB_SPIN(xb_ld(&bar[XB_TOPGEN]) == tg, bar);
;             __builtin_amdgcn_fence(__ATOMIC_ACQUIRE, "agent");
;             xb_add(&bar[XB_XGEN(b.x)], 1u);
;             asm volatile("s_waitcnt vmcnt(0)" ::: "memory");
;         } else {
;             XB_SPIN(xb_ld(&bar[XB_XGEN(b.x)]) == gen, bar);
.LBB0_103:
	s_and_b32 s24, s26, 0xff
	s_cmp_lg_u32 s24, 0
	s_mov_b64 s[38:39], -1
	s_sleep 4
	s_cbranch_scc0 .LBB0_106
	s_mov_b64 s[42:43], -1
	s_and_b64 vcc, exec, s[38:39]
	s_cbranch_vccz .LBB0_102

; __device__ __forceinline__ unsigned xb_ld(unsigned* p)              { return __hip_atomic_load(p, __ATOMIC_RELAXED, __HIP_MEMORY_SCOPE_AGENT); }
; __device__ __forceinline__ unsigned xb_add(unsigned* p, unsigned v) { return __hip_atomic_fetch_add(p, v, __ATOMIC_RELAXED, __HIP_MEMORY_SCOPE_AGENT); }
; #define XB_SPIN(cond, bar) do { unsigned _sp = 0; while (cond) { __builtin_amdgcn_s_sleep(1); \
;     if ((++_sp & 255u) == 0u) { if (xb_ld(&(bar)[XB_TMO])) break; if (_sp > XB_SPIN_CAP) { atomicAdd(&(bar)[XB_TMO], 1u); break; } } } } while (0)
; __device__ __forceinline__ void xcd_barrier(const XcdBarrier& b) {
;     ...
;             const unsigned og = xb_add(&bar[XB_TOP], 1u);
;             const unsigned tg = og / nx;
;             if (og + 1u == (tg + 1u) * nx) xb_add(&bar[XB_TOPGEN], 1u);
;             else XB_SPIN(xb_ld(&bar[XB_TOPGEN]) == tg, bar);
;             __builtin_amdgcn_fence(__ATOMIC_ACQUIRE, "agent");
;             xb_add(&bar[XB_XGEN(b.x)], 1u);
;             asm volatile("s_waitcnt vmcnt(0)" ::: "memory");
;         } else {
;             XB_SPIN(xb_ld(&bar[XB_XGEN(b.x)]) == gen, bar);
.LBB0_476:
	s_and_b32 s24, s26, 0xff
	s_mov_b64 s[22:23], -1
	s_cmp_lg_u32 s24, 0
	s_mov_b64 s[36:37], -1
	s_sleep 4
	s_cbranch_scc0 .LBB0_479
	s_and_b64 vcc, exec, s[36:37]
	s_cbranch_vccz .LBB0_475

; __device__ __forceinline__ unsigned xb_ld(unsigned* p)              { return __hip_atomic_load(p, __ATOMIC_RELAXED, __HIP_MEMORY_SCOPE_AGENT); }
; __device__ __forceinline__ unsigned xb_add(unsigned* p, unsigned v) { return __hip_atomic_fetch_add(p, v, __ATOMIC_RELAXED, __HIP_MEMORY_SCOPE_AGENT); }
; #define XB_SPIN(cond, bar) do { unsigned _sp = 0; while (cond) { __builtin_amdgcn_s_sleep(1); \
;     if ((++_sp & 255u) == 0u) { if (xb_ld(&(bar)[XB_TMO])) break; if (_sp > XB_SPIN_CAP) { atomicAdd(&(bar)[XB_TMO], 1u); break; } } } } while (0)
; __device__ __forceinline__ void xcd_barrier(const XcdBarrier& b) {
;     ...
;             const unsigned og = xb_add(&bar[XB_TOP], 1u);
;             const unsigned tg = og / nx;
;             if (og + 1u == (tg + 1u) * nx) xb_add(&bar[XB_TOPGEN], 1u);
;             else XB_SPIN(xb_ld(&bar[XB_TOPGEN]) == tg, bar);
;             __builtin_amdgcn_fence(__ATOMIC_ACQUIRE, "agent");
;             xb_add(&bar[XB_XGEN(b.x)], 1u);
;             asm volatile("s_waitcnt vmcnt(0)" ::: "memory");
;         } else {
;             XB_SPIN(xb_ld(&bar[XB_XGEN(b.x)]) == gen, bar);
.LBB0_493:
	s_and_b32 s24, s26, 0xff
	s_cmp_lg_u32 s24, 0
	s_mov_b64 s[36:37], -1
	s_sleep 4
	s_cbranch_scc0 .LBB0_496
	s_mov_b64 s[38:39], -1
	s_and_b64 vcc, exec, s[36:37]
	s_cbranch_vccz .LBB0_492

; __device__ __forceinline__ unsigned xb_ld(unsigned* p)              { return __hip_atomic_load(p, __ATOMIC_RELAXED, __HIP_MEMORY_SCOPE_AGENT); }
; __device__ __forceinline__ void xcd_barrier_complete(unsigned* bar, unsigned x, unsigned& nloc, unsigned& nx) {
;     const unsigned G = gridDim.x * gridDim.y * gridDim.z;
;     unsigned sum, cnt, mine, sp = 0u;
;     for (;;) {
;         sum = 0u; cnt = 0u; mine = 0u;
; #pragma unroll
;         for (unsigned j = 0; j < 16; ++j) { const unsigned c = xb_ld(&bar[XB_XCNT(j)]); sum += c; cnt += (c > 0u) ? 1u : 0u; mine = (j == x) ? c : mine; }
;         if (sum == G) break;
;         __builtin_amdgcn_s_sleep(1);
;         if ((++sp & 255u) == 0u) { if (xb_ld(&bar[XB_TMO])) break; if (sp > XB_SPIN_CAP) { atomicAdd(&bar[XB_TMO], 1u); break; } }
;     }
;     nloc = mine > 0u ? mine : 1u; nx = cnt > 0u ? cnt : 1u;
; }
.LBB0_624:
	global_load_dword v17, v18, s[34:35] offset:1024 sc1
	global_load_dword v2, v18, s[34:35] offset:1280 sc1
	global_load_dword v3, v18, s[34:35] offset:1536 sc1
	global_load_dword v4, v18, s[34:35] offset:1792 sc1
	global_load_dword v5, v18, s[34:35] offset:2048 sc1
	global_load_dword v6, v18, s[34:35] offset:2304 sc1
	global_load_dword v7, v18, s[34:35] offset:2560 sc1
	global_load_dword v8, v18, s[34:35] offset:2816 sc1
	global_load_dword v9, v18, s[34:35] offset:3072 sc1
	global_load_dword v10, v18, s[34:35] offset:3328 sc1
	global_load_dword v11, v18, s[34:35] offset:3584 sc1
	global_load_dword v12, v18, s[34:35] offset:3840 sc1
	global_load_dword v13, v18, s[2:3] sc1
	global_load_dword v14, v18, s[4:5] sc1
	global_load_dword v15, v18, s[6:7] sc1
	global_load_dword v16, v18, s[8:9] sc1
	s_mov_b64 s[10:11], -1
	s_mov_b64 s[12:13], -1
	s_waitcnt vmcnt(14)
	v_add_u32_e32 v19, v2, v17
	s_waitcnt vmcnt(13)
	v_add_u32_e32 v19, v19, v3
	s_waitcnt vmcnt(12)
	v_add_u32_e32 v19, v19, v4
	s_waitcnt vmcnt(11)
	v_add_u32_e32 v19, v19, v5
	s_waitcnt vmcnt(10)
	v_add_u32_e32 v19, v19, v6
	s_waitcnt vmcnt(9)
	v_add_u32_e32 v19, v19, v7
	s_waitcnt vmcnt(8)
	v_add_u32_e32 v19, v19, v8
	s_waitcnt vmcnt(7)
	v_add_u32_e32 v19, v19, v9
	s_waitcnt vmcnt(6)
	v_add_u32_e32 v19, v19, v10
	s_waitcnt vmcnt(5)
	v_add_u32_e32 v19, v19, v11
	s_waitcnt vmcnt(4)
	v_add_u32_e32 v19, v19, v12
	s_waitcnt vmcnt(3)
	v_add_u32_e32 v19, v19, v13
	s_waitcnt vmcnt(2)
	v_add_u32_e32 v19, v19, v14
	s_waitcnt vmcnt(1)
	v_add_u32_e32 v19, v19, v15
	s_waitcnt vmcnt(0)
	v_add_u32_e32 v19, v19, v16
	v_cmp_eq_u32_e32 vcc, s16, v19
	s_cbranch_vccnz .LBB0_623
	s_and_b32 s10, s17, 0xff
	s_cmp_eq_u32 s10, 0
	s_mov_b64 s[10:11], -1
	s_mov_b64 s[14:15], -1
	s_sleep 4
	s_cbranch_scc1 .LBB0_628
	s_and_b64 vcc, exec, s[14:15]
	s_cbranch_vccz .LBB0_623

; __device__ __forceinline__ unsigned xb_ld(unsigned* p)              { return __hip_atomic_load(p, __ATOMIC_RELAXED, __HIP_MEMORY_SCOPE_AGENT); }
; __device__ __forceinline__ unsigned xb_add(unsigned* p, unsigned v) { return __hip_atomic_fetch_add(p, v, __ATOMIC_RELAXED, __HIP_MEMORY_SCOPE_AGENT); }
; #define XB_SPIN(cond, bar) do { unsigned _sp = 0; while (cond) { __builtin_amdgcn_s_sleep(1); \
;     if ((++_sp & 255u) == 0u) { if (xb_ld(&(bar)[XB_TMO])) break; if (_sp > XB_SPIN_CAP) { atomicAdd(&(bar)[XB_TMO], 1u); break; } } } } while (0)
; __device__ __forceinline__ void xcd_barrier(const XcdBarrier& b) {
;     ...
;             const unsigned og = xb_add(&bar[XB_TOP], 1u);
;             const unsigned tg = og / nx;
;             if (og + 1u == (tg + 1u) * nx) xb_add(&bar[XB_TOPGEN], 1u);
;             else XB_SPIN(xb_ld(&bar[XB_TOPGEN]) == tg, bar);
;             __builtin_amdgcn_fence(__ATOMIC_ACQUIRE, "agent");
;             xb_add(&bar[XB_XGEN(b.x)], 1u);
;             asm volatile("s_waitcnt vmcnt(0)" ::: "memory");
;         } else {
;             XB_SPIN(xb_ld(&bar[XB_XGEN(b.x)]) == gen, bar);
.LBB0_642:
	s_and_b32 s16, s20, 0xff
	s_mov_b64 s[14:15], -1
	s_cmp_lg_u32 s16, 0
	s_mov_b64 s[18:19], -1
	s_sleep 4
	s_cbranch_scc0 .LBB0_645
	s_and_b64 vcc, exec, s[18:19]
	s_cbranch_vccz .LBB0_641

; __device__ __forceinline__ unsigned xb_ld(unsigned* p)              { return __hip_atomic_load(p, __ATOMIC_RELAXED, __HIP_MEMORY_SCOPE_AGENT); }
; __device__ __forceinline__ unsigned xb_add(unsigned* p, unsigned v) { return __hip_atomic_fetch_add(p, v, __ATOMIC_RELAXED, __HIP_MEMORY_SCOPE_AGENT); }
; #define XB_SPIN(cond, bar) do { unsigned _sp = 0; while (cond) { __builtin_amdgcn_s_sleep(1); \
;     if ((++_sp & 255u) == 0u) { if (xb_ld(&(bar)[XB_TMO])) break; if (_sp > XB_SPIN_CAP) { atomicAdd(&(bar)[XB_TMO], 1u); break; } } } } while (0)
; __device__ __forceinline__ void xcd_barrier(const XcdBarrier& b) {
;     ...
;             const unsigned og = xb_add(&bar[XB_TOP], 1u);
;             const unsigned tg = og / nx;
;             if (og + 1u == (tg + 1u) * nx) xb_add(&bar[XB_TOPGEN], 1u);
;             else XB_SPIN(xb_ld(&bar[XB_TOPGEN]) == tg, bar);
;             __builtin_amdgcn_fence(__ATOMIC_ACQUIRE, "agent");
;             xb_add(&bar[XB_XGEN(b.x)], 1u);
;             asm volatile("s_waitcnt vmcnt(0)" ::: "memory");
;         } else {
;             XB_SPIN(xb_ld(&bar[XB_XGEN(b.x)]) == gen, bar);
.LBB0_659:
	s_and_b32 s16, s22, 0xff
	s_cmp_lg_u32 s16, 0
	s_mov_b64 s[18:19], -1
	s_sleep 4
	s_cbranch_scc0 .LBB0_662
	s_mov_b64 s[20:21], -1
	s_and_b64 vcc, exec, s[18:19]
	s_cbranch_vccz .LBB0_658

; __global__ void __launch_bounds__(512, 2) fwd_kernel(Args a) {
;     ...
;     if (a.ph_hi < 0) cg::this_grid().sync();
.LBB0_2462:
	s_sleep 4
	global_load_dword v2, v0, s[2:3] offset:32 sc1
	s_waitcnt vmcnt(0)
	v_and_b32_e32 v2, 0xffff0000, v2
	v_cmp_ne_u32_e32 vcc, v2, v1
	s_or_b64 s[4:5], vcc, s[4:5]
	s_andn2_b64 exec, exec, s[4:5]
	s_cbranch_execnz .LBB0_2462
